# KIND2 window tiles: per-wave always-masked logits (12 of 32 per lane) skipped: bias reads, exps, packs, two PV MFMAs
# speedup vs baseline: 1.0080x; 1.0080x over previous
; #define MFMA(a, b, c) __builtin_amdgcn_mfma_f32_32x32x16_bf16((a), (b), (c), 0, 0, 0)
; DI void softmax_tile(f32x16 (&S)[2], float& lsum) {
;     f2_t ps = {0.f, 0.f};
; #pragma unroll
;     for (int t = 0; t < 2; ++t)
; #pragma unroll
;         for (int e = 0; e < 16; e += 2) {
;             f2_t pv; pv.x = __builtin_amdgcn_exp2f(S[t][e]); pv.y = __builtin_amdgcn_exp2f(S[t][e + 1]);
;             S[t][e] = pv.x; S[t][e + 1] = pv.y;
;             ps += pv;
;         }
;     lsum += ps.x + ps.y;
; }
; DI void pv_tile(const f32x16 (&S)[2], f32x16 (&O)[2], const bf16x8 (&vf)[8]) {
; #pragma unroll
;     for (int s = 0; s < 4; ++s) {
;         const bf16x8 pf = pack8(S[s >> 1], s & 1);
; #pragma unroll
;         for (int dt = 0; dt < 2; ++dt) O[dt] = MFMA(vf[2 * s + dt], pf, O[dt]);
;     }
; }
; template <int KIND>
; DI void attn_unit(const Params& p, int l, int b, int head, int qt, int qcol, int kcol, int vfeat, int gcol, int mixcol,
;                   int t1, int n1, int t2, int n2, char* smem) {
;     ...
;                 if (KIND == 2 && tile < 32) {
;                     const char* brow = smem + ATT_BIAS + (tile - nrow + 7) * 128;
; #pragma unroll
;                     for (int t = 0; t < 2; ++t)
; #pragma unroll
;                         for (int e = 0; e < 16; ++e) S[t][e] += *(const float*)(brow + bcol[t][e]);
;                 }
;                 softmax_tile(S, l0);
;                 pv_tile(S, O0, vf);
.LBB0_131:
	s_and_saveexec_b64 s[4:5], s[8:9]
	s_cbranch_execz .LBB0_135
	s_waitcnt lgkmcnt(0)
	v_mfma_f32_32x32x16_bf16 v[64:79], v[108:111], v[80:83], v[32:47]
	v_mfma_f32_32x32x16_bf16 v[48:63], v[104:107], v[80:83], v[32:47]
	v_mfma_f32_32x32x16_bf16 v[64:79], v[100:103], v[84:87], v[64:79]
	v_mfma_f32_32x32x16_bf16 v[48:63], v[96:99], v[84:87], v[48:63]
	v_mfma_f32_32x32x16_bf16 v[64:79], v[112:115], v[88:91], v[64:79]
	v_mfma_f32_32x32x16_bf16 v[48:63], v[116:119], v[88:91], v[48:63]
	v_mfma_f32_32x32x16_bf16 v[64:79], v[120:123], v[92:95], v[64:79]
	v_mfma_f32_32x32x16_bf16 v[48:63], v[124:127], v[92:95], v[48:63]
	s_andn2_b64 vcc, exec, s[6:7]
	s_cbranch_vccnz .Lk2_common
	v_readfirstlane_b32 s100, v200
	s_bitcmp1_b32 s100, 6
	s_cbranch_scc1 .Lk2_w1
	ds_read_b128 v[156:159], v131 offset:8192
	ds_read_b128 v[152:155], v131 offset:12288
	ds_read_b128 v[148:151], v130 offset:8192
	ds_read_b128 v[144:147], v130 offset:12288
	ds_read_b128 v[140:143], v129 offset:8192
	ds_read_b128 v[136:139], v129 offset:12288
	v_sub_u32_e32 v222, s56, v214
	v_lshl_add_u32 v246, v222, 7, 32
	v_add_u32_e32 v222, v246, v166
	v_add_u32_e32 v223, v246, v167
	v_add_u32_e32 v224, v246, v168
	v_add_u32_e32 v225, v246, v169
	v_add_u32_e32 v226, v246, v170
	v_add_u32_e32 v227, v246, v171
	v_add_u32_e32 v228, v246, v172
	v_add_u32_e32 v229, v246, v173
	v_add_u32_e32 v230, v246, v174
	v_add_u32_e32 v231, v246, v175
	v_add_u32_e32 v232, v246, v176
	v_add_u32_e32 v233, v246, v177
	v_add_u32_e32 v234, v246, v178
	v_add_u32_e32 v235, v246, v180
	v_add_u32_e32 v236, v246, v181
	v_add_u32_e32 v237, v246, v182
	v_add_u32_e32 v238, v246, v183
	v_add_u32_e32 v239, v246, v184
	v_add_u32_e32 v240, v246, v185
	v_add_u32_e32 v241, v246, v186
	ds_read_b32 v222, v222 offset:50048
	ds_read_b32 v223, v223 offset:50048
	ds_read_b32 v224, v224 offset:50048
	ds_read_b32 v225, v225 offset:50048
	ds_read_b32 v226, v226 offset:50048
	ds_read_b32 v227, v227 offset:50048
	ds_read_b32 v228, v228 offset:50048
	ds_read_b32 v229, v229 offset:50048
	ds_read_b32 v230, v230 offset:50048
	ds_read_b32 v231, v231 offset:50048
	ds_read_b32 v232, v232 offset:50048
	ds_read_b32 v233, v233 offset:50048
	ds_read_b32 v234, v234 offset:50048
	ds_read_b32 v235, v235 offset:50048
	ds_read_b32 v236, v236 offset:50048
	ds_read_b32 v237, v237 offset:50048
	ds_read_b32 v238, v238 offset:50048
	ds_read_b32 v239, v239 offset:50048
	ds_read_b32 v240, v240 offset:50048
	ds_read_b32 v241, v241 offset:50048
	s_waitcnt lgkmcnt(0)
	v_add_f32_e64 v76, v76, v234
	v_add_f32_e64 v77, v77, v235
	v_add_f32_e64 v78, v78, v236
	v_add_f32_e64 v79, v79, v237
	v_add_f32_e64 v74, v74, v232
	v_add_f32_e64 v75, v75, v233
	v_add_f32_e64 v72, v72, v230
	v_add_f32_e64 v73, v73, v231
	v_add_f32_e64 v70, v70, v228
	v_add_f32_e64 v71, v71, v229
	v_add_f32_e64 v68, v68, v226
	v_add_f32_e64 v69, v69, v227
	v_add_f32_e64 v66, v66, v224
	v_add_f32_e64 v67, v67, v225
	v_add_f32_e64 v64, v64, v222
	v_add_f32_e64 v65, v65, v223
	v_add_f32_e64 v50, v50, v240
	v_add_f32_e64 v51, v51, v241
	v_add_f32_e64 v48, v48, v238
	v_add_f32_e64 v49, v49, v239
	s_nop 0
	v_exp_f32_e32 v64, v64
	v_exp_f32_e32 v65, v65
	v_exp_f32_e32 v66, v66
	v_exp_f32_e32 v67, v67
	v_exp_f32_e32 v68, v68
	v_exp_f32_e32 v69, v69
	v_exp_f32_e32 v70, v70
	v_exp_f32_e32 v71, v71
	v_add_f32_e64 v222, v64, 0
	v_add_f32_e64 v223, v65, 0
	v_cvt_pk_bf16_f32 v64, v64, v65
	v_add_f32_e64 v222, v66, v222
	v_add_f32_e64 v223, v67, v223
	v_cvt_pk_bf16_f32 v65, v66, v67
	v_cvt_pk_bf16_f32 v66, v68, v69
	v_cvt_pk_bf16_f32 v67, v70, v71
	v_add_f32_e64 v222, v68, v222
	v_add_f32_e64 v223, v69, v223
	v_exp_f32_e32 v72, v72
	s_waitcnt lgkmcnt(0)
	v_mfma_f32_32x32x16_bf16 v[16:31], v[156:159], v[64:67], v[16:31]
	v_exp_f32_e32 v73, v73
	v_add_f32_e64 v68, v70, v222
	v_add_f32_e64 v69, v71, v223
	v_exp_f32_e32 v70, v74
	v_exp_f32_e32 v71, v75
	v_exp_f32_e32 v74, v76
	v_exp_f32_e32 v75, v77
	v_exp_f32_e32 v76, v78
	v_mfma_f32_32x32x16_bf16 v[0:15], v[152:155], v[64:67], v[0:15]
	v_exp_f32_e32 v77, v79
	v_cvt_pk_bf16_f32 v64, v72, v73
	v_cvt_pk_bf16_f32 v65, v70, v71
	v_cvt_pk_bf16_f32 v66, v74, v75
	v_cvt_pk_bf16_f32 v67, v76, v77
	v_add_f32_e64 v68, v72, v68
	v_add_f32_e64 v69, v73, v69
	v_exp_f32_e32 v48, v48
	v_mfma_f32_32x32x16_bf16 v[16:31], v[148:151], v[64:67], v[16:31]
	v_exp_f32_e32 v49, v49
	v_add_f32_e64 v68, v70, v68
	v_add_f32_e64 v69, v71, v69
	v_exp_f32_e32 v70, v50
	v_exp_f32_e32 v71, v51
	v_mfma_f32_32x32x16_bf16 v[0:15], v[144:147], v[64:67], v[0:15]
	v_add_f32_e64 v68, v74, v68
	v_add_f32_e64 v69, v75, v69
	v_mov_b32_e32 v50, 0
	v_add_f32_e64 v68, v76, v68
	v_add_f32_e64 v69, v77, v69
	v_mov_b32_e32 v51, 0
	v_add_f32_e64 v68, v48, v68
	v_add_f32_e64 v69, v49, v69
	v_cvt_pk_bf16_f32 v48, v48, v49
	v_cvt_pk_bf16_f32 v49, v70, v71
	s_nop 1
	v_mfma_f32_32x32x16_bf16 v[16:31], v[140:143], v[48:51], v[16:31]
	v_add_f32_e64 v64, v70, v68
	v_add_f32_e64 v65, v71, v69
	v_mfma_f32_32x32x16_bf16 v[0:15], v[136:139], v[48:51], v[0:15]
	v_add_f32_e32 v52, v64, v65
	v_add_f32_e32 v179, v179, v52
	s_branch .LBB0_135
; #define MFMA(a, b, c) __builtin_amdgcn_mfma_f32_32x32x16_bf16((a), (b), (c), 0, 0, 0)
; DI void softmax_tile(f32x16 (&S)[2], float& lsum) {
;     f2_t ps = {0.f, 0.f};
; #pragma unroll
;     for (int t = 0; t < 2; ++t)
; #pragma unroll
;         for (int e = 0; e < 16; e += 2) {
;             f2_t pv; pv.x = __builtin_amdgcn_exp2f(S[t][e]); pv.y = __builtin_amdgcn_exp2f(S[t][e + 1]);
;             S[t][e] = pv.x; S[t][e + 1] = pv.y;
;             ps += pv;
;         }
;     lsum += ps.x + ps.y;
; }
; DI void pv_tile(const f32x16 (&S)[2], f32x16 (&O)[2], const bf16x8 (&vf)[8]) {
; #pragma unroll
;     for (int s = 0; s < 4; ++s) {
;         const bf16x8 pf = pack8(S[s >> 1], s & 1);
; #pragma unroll
;         for (int dt = 0; dt < 2; ++dt) O[dt] = MFMA(vf[2 * s + dt], pf, O[dt]);
;     }
; }
; template <int KIND>
; DI void attn_unit(const Params& p, int l, int b, int head, int qt, int qcol, int kcol, int vfeat, int gcol, int mixcol,
;                   int t1, int n1, int t2, int n2, char* smem) {
;     ...
;                 if (KIND == 2 && tile < 32) {
;                     const char* brow = smem + ATT_BIAS + (tile - nrow + 7) * 128;
; #pragma unroll
;                     for (int t = 0; t < 2; ++t)
; #pragma unroll
;                         for (int e = 0; e < 16; ++e) S[t][e] += *(const float*)(brow + bcol[t][e]);
;                 }
;                 softmax_tile(S, l0);
;                 pv_tile(S, O0, vf);
.Lk2_w1:
	ds_read_b128 v[148:151], v130 offset:8192
	ds_read_b128 v[144:147], v130 offset:12288
	ds_read_b128 v[140:143], v129 offset:8192
	ds_read_b128 v[136:139], v129 offset:12288
	ds_read_b128 v[132:135], v128 offset:8192
	ds_read_b128 v[128:131], v128 offset:12288
	v_sub_u32_e32 v222, s56, v214
	v_lshl_add_u32 v246, v222, 7, 32
	v_add_u32_e32 v234, v246, v178
	v_add_u32_e32 v235, v246, v180
	v_add_u32_e32 v236, v246, v181
	v_add_u32_e32 v237, v246, v182
	v_add_u32_e32 v238, v246, v183
	v_add_u32_e32 v239, v246, v184
	v_add_u32_e32 v240, v246, v185
	v_add_u32_e32 v241, v246, v186
	v_add_u32_e32 v242, v246, v187
	v_add_u32_e32 v243, v246, v188
	v_add_u32_e32 v244, v246, v189
	v_add_u32_e32 v245, v246, v190
	v_add_u32_e32 v247, v246, v191
	v_add_u32_e32 v248, v246, v192
	v_add_u32_e32 v249, v246, v194
	v_add_u32_e32 v250, v246, v195
	v_add_u32_e32 v251, v246, v196
	v_add_u32_e32 v252, v246, v197
	v_add_u32_e32 v253, v246, v198
	ds_read_b32 v234, v234 offset:50048
	ds_read_b32 v235, v235 offset:50048
	ds_read_b32 v236, v236 offset:50048
	ds_read_b32 v237, v237 offset:50048
	ds_read_b32 v238, v238 offset:50048
	ds_read_b32 v239, v239 offset:50048
	ds_read_b32 v240, v240 offset:50048
	ds_read_b32 v241, v241 offset:50048
	ds_read_b32 v242, v242 offset:50048
	ds_read_b32 v243, v243 offset:50048
	ds_read_b32 v244, v244 offset:50048
	ds_read_b32 v245, v245 offset:50048
	v_add_u32_e32 v210, v246, v199
	ds_read_b32 v246, v247 offset:50048
	ds_read_b32 v247, v248 offset:50048
	ds_read_b32 v248, v249 offset:50048
	ds_read_b32 v249, v250 offset:50048
	ds_read_b32 v250, v251 offset:50048
	ds_read_b32 v251, v252 offset:50048
	ds_read_b32 v252, v253 offset:50048
	ds_read_b32 v253, v210 offset:50048
	s_waitcnt lgkmcnt(0)
	v_add_f32_e64 v76, v76, v234
	v_add_f32_e64 v77, v77, v235
	v_add_f32_e64 v78, v78, v236
	v_add_f32_e64 v79, v79, v237
	v_add_f32_e64 v62, v62, v252
	v_add_f32_e64 v63, v63, v253
	v_add_f32_e64 v60, v60, v250
	v_add_f32_e64 v61, v61, v251
	v_add_f32_e64 v58, v58, v248
	v_add_f32_e64 v59, v59, v249
	v_add_f32_e64 v56, v56, v246
	v_add_f32_e64 v57, v57, v247
	v_add_f32_e64 v54, v54, v244
	v_add_f32_e64 v55, v55, v245
	v_add_f32_e64 v52, v52, v242
	v_add_f32_e64 v53, v53, v243
	v_add_f32_e64 v50, v50, v240
	v_add_f32_e64 v51, v51, v241
	v_add_f32_e64 v48, v48, v238
	v_add_f32_e64 v49, v49, v239
	s_nop 0
	s_waitcnt lgkmcnt(0)
	v_exp_f32_e32 v74, v76
	v_exp_f32_e32 v75, v77
	v_exp_f32_e32 v76, v78
	v_exp_f32_e32 v77, v79
	v_mov_b32_e32 v64, 0
	v_mov_b32_e32 v65, 0
	v_cvt_pk_bf16_f32 v66, v74, v75
	v_cvt_pk_bf16_f32 v67, v76, v77
	v_exp_f32_e32 v48, v48
	s_nop 0
	v_mfma_f32_32x32x16_bf16 v[16:31], v[148:151], v[64:67], v[16:31]
	v_exp_f32_e32 v49, v49
	v_exp_f32_e32 v70, v50
	v_exp_f32_e32 v71, v51
	v_exp_f32_e32 v52, v52
	v_exp_f32_e32 v53, v53
	v_exp_f32_e32 v54, v54
	v_mfma_f32_32x32x16_bf16 v[0:15], v[144:147], v[64:67], v[0:15]
	v_exp_f32_e32 v55, v55
	v_add_f32_e64 v68, v74, 0
	v_add_f32_e64 v69, v75, 0
	v_cvt_pk_bf16_f32 v50, v52, v53
	v_add_f32_e64 v68, v76, v68
	v_add_f32_e64 v69, v77, v69
	v_cvt_pk_bf16_f32 v51, v54, v55
	v_add_f32_e64 v68, v48, v68
	v_add_f32_e64 v69, v49, v69
	v_cvt_pk_bf16_f32 v48, v48, v49
	v_cvt_pk_bf16_f32 v49, v70, v71
	v_exp_f32_e32 v56, v56
	v_exp_f32_e32 v57, v57
	v_mfma_f32_32x32x16_bf16 v[16:31], v[140:143], v[48:51], v[16:31]
	v_exp_f32_e32 v58, v58
	v_exp_f32_e32 v59, v59
	v_exp_f32_e32 v60, v60
	v_exp_f32_e32 v61, v61
	v_exp_f32_e32 v62, v62
	v_exp_f32_e32 v63, v63
	v_add_f32_e64 v64, v70, v68
	v_add_f32_e64 v65, v71, v69
	v_mfma_f32_32x32x16_bf16 v[0:15], v[136:139], v[48:51], v[0:15]
	v_cvt_pk_bf16_f32 v48, v56, v57
	v_cvt_pk_bf16_f32 v49, v58, v59
	v_cvt_pk_bf16_f32 v50, v60, v61
	v_cvt_pk_bf16_f32 v51, v62, v63
	v_add_f32_e64 v52, v52, v64
	v_add_f32_e64 v53, v53, v65
	v_add_f32_e64 v52, v54, v52
	v_add_f32_e64 v53, v55, v53
	v_mfma_f32_32x32x16_bf16 v[16:31], v[132:135], v[48:51], v[16:31]
	v_add_f32_e64 v52, v56, v52
	v_add_f32_e64 v53, v57, v53
	v_add_f32_e64 v52, v58, v52
	v_add_f32_e64 v53, v59, v53
	v_add_f32_e64 v52, v60, v52
	v_add_f32_e64 v53, v61, v53
	v_add_f32_e64 v52, v62, v52
	v_add_f32_e64 v53, v63, v53
	v_mfma_f32_32x32x16_bf16 v[0:15], v[128:131], v[48:51], v[0:15]
	v_add_f32_e32 v52, v52, v53
	v_add_f32_e32 v179, v179, v52
	s_branch .LBB0_135
; #define MFMA(a, b, c) __builtin_amdgcn_mfma_f32_32x32x16_bf16((a), (b), (c), 0, 0, 0)
; #define LOAD_VF() do { \
;             __builtin_amdgcn_sched_barrier(0); \
;             _Pragma("unroll") for (int s = 0; s < 4; ++s) \
;                 _Pragma("unroll") for (int dt = 0; dt < 2; ++dt) vf[2 * s + dt] = ldv_frag(sv, 32 * dt + r, 2 * s + h, xr); \
;             __builtin_amdgcn_sched_barrier(0); } while (0)
; template <int KIND>
; DI void attn_unit(const Params& p, int l, int b, int head, int qt, int qcol, int kcol, int vfeat, int gcol, int mixcol,
;                   int t1, int n1, int t2, int n2, char* smem) {
;     ...
;             if (KIND == 0) {
;                 f32x16 S0[2], S1[2];
; #pragma unroll
;                 for (int t = 0; t < 2; ++t) { S0[t] = MFMA(kf[t], qf[0], cz); S1[t] = MFMA(kf[4 + t], qf[2], cz); }
; #pragma unroll
;                 for (int t = 0; t < 2; ++t) { S0[t] = MFMA(kf[2 + t], qf[1], S0[t]); S1[t] = MFMA(kf[6 + t], qf[3], S1[t]); }
;                 LOAD_VF();
;                 softmax_tile(S0, l0);
;                 pv_tile(S0, O0, vf);
;                 softmax_tile(S1, l1);
;                 pv_tile(S1, O1, vf);
;             } else {
;                 f32x16 S[2];
; #pragma unroll
;                 for (int t = 0; t < 2; ++t) S[t] = MFMA(kf[t], qf[0], cz);
; #pragma unroll
;                 for (int s = 1; s < 4; ++s)
; #pragma unroll
;                     for (int t = 0; t < 2; ++t) S[t] = MFMA(kf[2 * s + t], qf[s], S[t]);
;                 LOAD_VF();
;                 if (KIND == 2 && tile < 32) {
;                     const char* brow = smem + ATT_BIAS + (tile - nrow + 7) * 128;
; #pragma unroll
;                     for (int t = 0; t < 2; ++t)
; #pragma unroll
;                         for (int e = 0; e < 16; ++e) S[t][e] += *(const float*)(brow + bcol[t][e]);
.Lk2_common:
	ds_read_b128 v[156:159], v131 offset:8192
	ds_read_b128 v[152:155], v131 offset:12288
	ds_read_b128 v[148:151], v130 offset:8192
	ds_read_b128 v[144:147], v130 offset:12288
	ds_read_b128 v[140:143], v129 offset:8192
	ds_read_b128 v[136:139], v129 offset:12288
	ds_read_b128 v[132:135], v128 offset:8192
	ds_read_b128 v[128:131], v128 offset:12288
	s_andn2_b64 vcc, exec, s[6:7]
	s_cbranch_vccnz .LBB0_134
	v_sub_u32_e32 v222, s56, v214
	v_lshl_add_u32 v246, v222, 7, 32
	v_add_u32_e32 v222, v246, v166
	v_add_u32_e32 v223, v246, v167
	v_add_u32_e32 v224, v246, v168
	v_add_u32_e32 v225, v246, v169
	v_add_u32_e32 v226, v246, v170
	v_add_u32_e32 v227, v246, v171
	v_add_u32_e32 v228, v246, v172
	v_add_u32_e32 v229, v246, v173
	v_add_u32_e32 v230, v246, v174
	v_add_u32_e32 v231, v246, v175
	v_add_u32_e32 v232, v246, v176
	v_add_u32_e32 v233, v246, v177
	v_add_u32_e32 v234, v246, v178
	v_add_u32_e32 v235, v246, v180
	v_add_u32_e32 v236, v246, v181
	v_add_u32_e32 v237, v246, v182
	v_add_u32_e32 v238, v246, v183
	v_add_u32_e32 v239, v246, v184
	v_add_u32_e32 v240, v246, v185
	v_add_u32_e32 v241, v246, v186
	v_add_u32_e32 v242, v246, v187
	v_add_u32_e32 v243, v246, v188
	v_add_u32_e32 v244, v246, v189
	v_add_u32_e32 v245, v246, v190
	v_add_u32_e32 v247, v246, v191
	v_add_u32_e32 v248, v246, v192
	v_add_u32_e32 v249, v246, v194
	v_add_u32_e32 v250, v246, v195
	v_add_u32_e32 v251, v246, v196
	v_add_u32_e32 v252, v246, v197
	v_add_u32_e32 v253, v246, v198
	ds_read_b32 v222, v222 offset:50048
	ds_read_b32 v223, v223 offset:50048
	ds_read_b32 v224, v224 offset:50048
	ds_read_b32 v225, v225 offset:50048
	ds_read_b32 v226, v226 offset:50048
	ds_read_b32 v227, v227 offset:50048
	ds_read_b32 v228, v228 offset:50048
	ds_read_b32 v229, v229 offset:50048
	ds_read_b32 v230, v230 offset:50048
	ds_read_b32 v231, v231 offset:50048
	ds_read_b32 v232, v232 offset:50048
	ds_read_b32 v233, v233 offset:50048
	ds_read_b32 v234, v234 offset:50048
	ds_read_b32 v235, v235 offset:50048
	ds_read_b32 v236, v236 offset:50048
	ds_read_b32 v237, v237 offset:50048
	ds_read_b32 v238, v238 offset:50048
	ds_read_b32 v239, v239 offset:50048
	ds_read_b32 v240, v240 offset:50048
	ds_read_b32 v241, v241 offset:50048
	ds_read_b32 v242, v242 offset:50048
	ds_read_b32 v243, v243 offset:50048
	ds_read_b32 v244, v244 offset:50048
	ds_read_b32 v245, v245 offset:50048
	v_add_u32_e32 v210, v246, v199
	ds_read_b32 v246, v247 offset:50048
	ds_read_b32 v247, v248 offset:50048
	ds_read_b32 v248, v249 offset:50048
	ds_read_b32 v249, v250 offset:50048
	ds_read_b32 v250, v251 offset:50048
	ds_read_b32 v251, v252 offset:50048
	ds_read_b32 v252, v253 offset:50048
	ds_read_b32 v253, v210 offset:50048
	s_waitcnt lgkmcnt(0)
	v_add_f32_e64 v76, v76, v234
	v_add_f32_e64 v77, v77, v235
	v_add_f32_e64 v78, v78, v236
	v_add_f32_e64 v79, v79, v237
	v_add_f32_e64 v74, v74, v232
	v_add_f32_e64 v75, v75, v233
	v_add_f32_e64 v72, v72, v230
	v_add_f32_e64 v73, v73, v231
	v_add_f32_e64 v70, v70, v228
	v_add_f32_e64 v71, v71, v229
	v_add_f32_e64 v68, v68, v226
	v_add_f32_e64 v69, v69, v227
	v_add_f32_e64 v66, v66, v224
	v_add_f32_e64 v67, v67, v225
	v_add_f32_e64 v64, v64, v222
	v_add_f32_e64 v65, v65, v223
	v_add_f32_e64 v62, v62, v252
	v_add_f32_e64 v63, v63, v253
	v_add_f32_e64 v60, v60, v250
	v_add_f32_e64 v61, v61, v251
	v_add_f32_e64 v58, v58, v248
	v_add_f32_e64 v59, v59, v249
	v_add_f32_e64 v56, v56, v246
	v_add_f32_e64 v57, v57, v247
	v_add_f32_e64 v54, v54, v244
	v_add_f32_e64 v55, v55, v245
	v_add_f32_e64 v52, v52, v242
	v_add_f32_e64 v53, v53, v243
	v_add_f32_e64 v50, v50, v240
	v_add_f32_e64 v51, v51, v241
	v_add_f32_e64 v48, v48, v238
	v_add_f32_e64 v49, v49, v239
